# speedup vs baseline: 1.0090x; 1.0031x over previous
.LBB0_164:
	s_cmp_lt_u32 s60, 8
	s_cselect_b64 s[74:75], -1, 0
	s_bitcmp1_b32 s60, 0
	s_cselect_b32 s60, 0x8800, 0
	s_add_i32 s60, s60, 0
	v_add_u32_e32 v0, s60, v119
	v_add_u32_e32 v102, v0, v118
	v_add_u32_e32 v101, v0, v120
	ds_read_b128 v[68:71], v102
	ds_read_b128 v[72:75], v102 offset:4096
	ds_read_b128 v[76:79], v101
	ds_read_b128 v[80:83], v101 offset:4096
	s_waitcnt lgkmcnt(3)
	v_mfma_f32_16x16x32_bf16 v[68:71], v[68:71], v[4:7], 0
	v_add_u32_e32 v139, v0, v121
	v_add_u32_e32 v137, v0, v122
	v_add_u32_e32 v0, s60, v117
	s_waitcnt lgkmcnt(1)
	v_mfma_f32_16x16x32_bf16 v[68:71], v[76:79], v[8:11], v[68:71]
	ds_read_b128 v[76:79], v139
	v_add_u32_e32 v155, v0, v123
	s_movk_i32 s60, 0xfefe
	v_mfma_f32_16x16x32_bf16 v[72:75], v[72:75], v[4:7], 0
	v_add_u32_e32 v2, 0x4000, v155
	v_add_u32_e32 v100, 0x4800, v155
	v_add_u32_e32 v3, 0x5000, v155
	s_waitcnt lgkmcnt(1)
	v_mfma_f32_16x16x32_bf16 v[72:75], v[80:83], v[8:11], v[72:75]
	ds_read_b128 v[80:83], v137
	ds_read_b128 v[84:87], v139 offset:4096
	ds_read_b128 v[88:91], v137 offset:4096
	v_add_u32_e32 v135, 0x5800, v155
	s_waitcnt lgkmcnt(3)
	v_mfma_f32_16x16x32_bf16 v[68:71], v[76:79], v[12:15], v[68:71]
	v_add_u32_e32 v136, 0x6000, v155
	v_add_u32_e32 v138, 0x6800, v155
	v_add_u32_e32 v103, 0x7000, v155
	s_waitcnt lgkmcnt(2)
	v_mfma_f32_16x16x32_bf16 v[68:71], v[80:83], v[16:19], v[68:71]
	v_add_u32_e32 v155, 0x7800, v155
	ds_read2_b64 v[76:79], v2 offset1:4
	ds_read2_b64 v[80:83], v100 offset0:32 offset1:36
	s_waitcnt lgkmcnt(3)
	v_mfma_f32_16x16x32_bf16 v[72:75], v[84:87], v[12:15], v[72:75]
	ds_read2_b64 v[84:87], v3 offset0:64 offset1:68
	s_nop 1
	v_mul_f32_e32 v0, 0x3e0293ee, v68
	v_add_u32_e32 v68, 51, v125
	v_cmp_gt_u32_e32 vcc, s82, v68
	v_add_u32_e32 v68, s58, v124
	s_or_b64 vcc, s[74:75], vcc
	v_add_u32_e32 v68, 0xfffffcc0, v68
	v_cndmask_b32_e32 v127, v210, v0, vcc
	v_cmp_lt_u32_e32 vcc, s60, v68
	v_mul_f32_e32 v0, 0x3e0293ee, v69
	s_or_b64 vcc, s[74:75], vcc
	v_add_u32_e32 v68, 49, v125
	v_cndmask_b32_e32 v128, v210, v0, vcc
	v_cmp_gt_u32_e32 vcc, s82, v68
	s_waitcnt lgkmcnt(3)
	v_mfma_f32_16x16x32_bf16 v[72:75], v[88:91], v[16:19], v[72:75]
	v_mul_f32_e32 v0, 0x3e0293ee, v70
	s_or_b64 vcc, s[74:75], vcc
	v_add_u32_e32 v68, 48, v125
	v_cndmask_b32_e32 v129, v210, v0, vcc
	v_cmp_gt_u32_e32 vcc, s82, v68
	v_mul_f32_e32 v0, 0x3e0293ee, v71
	s_or_b64 vcc, s[74:75], vcc
	v_add_u32_e32 v68, 35, v125
	v_cndmask_b32_e32 v130, v210, v0, vcc
	v_cmp_gt_u32_e32 vcc, s82, v68
	v_mul_f32_e32 v0, 0x3e0293ee, v72
	s_or_b64 vcc, s[74:75], vcc
	v_add_u32_e32 v68, 34, v125
	v_cndmask_b32_e32 v131, v210, v0, vcc
	v_cmp_gt_u32_e32 vcc, s82, v68
	v_mul_f32_e32 v0, 0x3e0293ee, v73
	s_or_b64 vcc, s[74:75], vcc
	v_add_u32_e32 v68, 33, v125
	v_cndmask_b32_e32 v132, v210, v0, vcc
	v_cmp_gt_u32_e32 vcc, s82, v68
	v_mul_f32_e32 v0, 0x3e0293ee, v74
	s_or_b64 vcc, s[74:75], vcc
	v_add_u32_e32 v68, 32, v125
	v_cndmask_b32_e32 v133, v210, v0, vcc
	v_cmp_gt_u32_e32 vcc, s82, v68
	v_mul_f32_e32 v0, 0x3e0293ee, v75
	s_or_b64 vcc, s[74:75], vcc
	v_cndmask_b32_e32 v134, v210, v0, vcc
	v_max_f32_e32 v69, v133, v134
	v_max_f32_e32 v0, v127, v128
	v_max_f32_e32 v68, v129, v130
	v_max3_f32 v69, v131, v132, v69
	v_max3_f32 v0, v0, v68, v69
	v_mov_b32_e32 v68, v0
	ds_read2_b64 v[88:91], v135 offset0:96 offset1:100
	ds_read2_b64 v[92:95], v136 offset0:128 offset1:132
	ds_read2_b64 v[96:99], v138 offset0:160 offset1:164
	ds_read2_b64 v[72:75], v103 offset0:192 offset1:196
	s_waitcnt lgkmcnt(4)
	v_permlane16_swap_b32_e32 v68, v0
	v_max_f32_e32 v0, v0, v68
	v_mov_b32_e32 v68, v0
	s_waitcnt lgkmcnt(0)
	s_nop 0
	v_permlane32_swap_b32_e32 v68, v0
	v_max_f32_e32 v0, v0, v68
	v_add_f32_e32 v68, 0x41000000, v126
	v_cmp_gt_f32_e32 vcc, v0, v68
	s_cmp_eq_u64 vcc, 0
	v_max_f32_e32 v68, v126, v126
	v_max_f32_e32 v0, v68, v0
	s_cselect_b64 vcc, -1, 0
	v_cndmask_b32_e32 v154, v0, v126, vcc
	v_sub_f32_e32 v0, v126, v154
	v_exp_f32_e32 v0, v0
	ds_read2_b64 v[68:71], v155 offset0:224 offset1:228
	v_cmp_neq_f32_e32 vcc, 1.0, v0
	s_cbranch_vccz .LBB0_166
	v_pk_mul_f32 v[66:67], v[66:67], v[0:1] op_sel_hi:[1,0]
	v_pk_mul_f32 v[64:65], v[64:65], v[0:1] op_sel_hi:[1,0]
	v_pk_mul_f32 v[62:63], v[62:63], v[0:1] op_sel_hi:[1,0]
	v_pk_mul_f32 v[60:61], v[60:61], v[0:1] op_sel_hi:[1,0]
	v_pk_mul_f32 v[58:59], v[58:59], v[0:1] op_sel_hi:[1,0]
	v_pk_mul_f32 v[56:57], v[56:57], v[0:1] op_sel_hi:[1,0]
	v_pk_mul_f32 v[54:55], v[54:55], v[0:1] op_sel_hi:[1,0]
	v_pk_mul_f32 v[52:53], v[52:53], v[0:1] op_sel_hi:[1,0]
	v_pk_mul_f32 v[50:51], v[50:51], v[0:1] op_sel_hi:[1,0]
	v_pk_mul_f32 v[48:49], v[48:49], v[0:1] op_sel_hi:[1,0]
	v_pk_mul_f32 v[46:47], v[46:47], v[0:1] op_sel_hi:[1,0]
	v_pk_mul_f32 v[44:45], v[44:45], v[0:1] op_sel_hi:[1,0]
	v_pk_mul_f32 v[42:43], v[42:43], v[0:1] op_sel_hi:[1,0]
	v_pk_mul_f32 v[40:41], v[40:41], v[0:1] op_sel_hi:[1,0]
	v_pk_mul_f32 v[38:39], v[38:39], v[0:1] op_sel_hi:[1,0]
	v_pk_mul_f32 v[36:37], v[36:37], v[0:1] op_sel_hi:[1,0]
.LBB0_166:
	v_sub_f32_e32 v126, v127, v154
	v_exp_f32_e32 v127, v126
	v_sub_f32_e32 v126, v128, v154
	v_exp_f32_e32 v128, v126
	v_sub_f32_e32 v126, v129, v154
	v_exp_f32_e32 v129, v126
	v_sub_f32_e32 v126, v130, v154
	v_exp_f32_e32 v130, v126
	v_sub_f32_e32 v126, v131, v154
	v_exp_f32_e32 v131, v126
	v_sub_f32_e32 v126, v132, v154
	v_exp_f32_e32 v132, v126
	v_sub_f32_e32 v126, v133, v154
	v_exp_f32_e32 v133, v126
	v_sub_f32_e32 v126, v134, v154
	v_exp_f32_e32 v134, v126
	v_cvt_pk_bf16_f32 v164, v127, v128
	v_cvt_pk_bf16_f32 v165, v129, v130
	v_cvt_pk_bf16_f32 v166, v131, v132
	v_cvt_pk_bf16_f32 v167, v133, v134
	s_nop 1
	v_mfma_f32_16x16x32_bf16 v[64:67], v[76:79], v[164:167], v[64:67]
	v_mfma_f32_16x16x32_bf16 v[60:63], v[80:83], v[164:167], v[60:63]
	ds_read_b128 v[76:79], v102 offset:8192
	ds_read_b128 v[80:83], v102 offset:12288
	v_mfma_f32_16x16x32_bf16 v[56:59], v[84:87], v[164:167], v[56:59]
	v_mfma_f32_16x16x32_bf16 v[52:55], v[88:91], v[164:167], v[52:55]
	ds_read_b128 v[84:87], v101 offset:8192
	ds_read_b128 v[88:91], v101 offset:12288
	s_waitcnt lgkmcnt(3)
	v_mfma_f32_16x16x32_bf16 v[76:79], v[76:79], v[4:7], 0
	v_mfma_f32_16x16x32_bf16 v[48:51], v[92:95], v[164:167], v[48:51]
	s_waitcnt lgkmcnt(1)
	v_mfma_f32_16x16x32_bf16 v[76:79], v[84:87], v[8:11], v[76:79]
	ds_read_b128 v[84:87], v139 offset:8192
	ds_read_b128 v[92:95], v139 offset:12288
	v_mfma_f32_16x16x32_bf16 v[44:47], v[96:99], v[164:167], v[44:47]
	s_waitcnt lgkmcnt(1)
	v_mfma_f32_16x16x32_bf16 v[76:79], v[84:87], v[12:15], v[76:79]
	ds_read_b128 v[84:87], v137 offset:8192
	ds_read_b128 v[96:99], v137 offset:12288
	v_mfma_f32_16x16x32_bf16 v[80:83], v[80:83], v[4:7], 0
	s_waitcnt lgkmcnt(1)
	v_mfma_f32_16x16x32_bf16 v[76:79], v[84:87], v[16:19], v[76:79]
	v_add_u32_e32 v84, 19, v125
	v_cmp_gt_u32_e32 vcc, s82, v84
	s_or_b64 vcc, s[74:75], vcc
	v_mfma_f32_16x16x32_bf16 v[80:83], v[88:91], v[8:11], v[80:83]
	v_mfma_f32_16x16x32_bf16 v[80:83], v[92:95], v[12:15], v[80:83]
	s_nop 2
	v_mul_f32_e32 v76, 0x3e0293ee, v76
	v_cndmask_b32_e32 v137, v210, v76, vcc
	v_mul_f32_e32 v76, 0x3e0293ee, v77
	v_add_u32_e32 v77, 18, v125
	v_cmp_gt_u32_e32 vcc, s82, v77
	s_or_b64 vcc, s[74:75], vcc
	v_add_u32_e32 v77, 17, v125
	v_cndmask_b32_e32 v139, v210, v76, vcc
	v_cmp_gt_u32_e32 vcc, s82, v77
	v_mul_f32_e32 v76, 0x3e0293ee, v78
	s_waitcnt lgkmcnt(0)
	v_mfma_f32_16x16x32_bf16 v[80:83], v[96:99], v[16:19], v[80:83]
	s_or_b64 vcc, s[74:75], vcc
	v_add_u32_e32 v77, 16, v125
	v_cndmask_b32_e32 v156, v210, v76, vcc
	v_cmp_gt_u32_e32 vcc, s82, v77
	v_mul_f32_e32 v76, 0x3e0293ee, v79
	s_or_b64 vcc, s[74:75], vcc
	v_add_u32_e32 v77, 3, v125
	v_cndmask_b32_e32 v157, v210, v76, vcc
	v_cmp_gt_u32_e32 vcc, s82, v77
	v_mul_f32_e32 v76, 0x3e0293ee, v80
	s_or_b64 vcc, s[74:75], vcc
	v_add_u32_e32 v77, 2, v125
	v_cndmask_b32_e32 v158, v210, v76, vcc
	v_cmp_gt_u32_e32 vcc, s82, v77
	v_mul_f32_e32 v76, 0x3e0293ee, v81
	s_or_b64 vcc, s[74:75], vcc
	v_add_u32_e32 v77, 1, v125
	v_cndmask_b32_e32 v159, v210, v76, vcc
	v_cmp_gt_u32_e32 vcc, s82, v77
	v_mul_f32_e32 v76, 0x3e0293ee, v82
	s_or_b64 vcc, s[74:75], vcc
	v_cndmask_b32_e32 v160, v210, v76, vcc
	v_cmp_gt_u32_e32 vcc, s82, v125
	v_mul_f32_e32 v76, 0x3e0293ee, v83
	s_or_b64 vcc, s[74:75], vcc
	v_cndmask_b32_e32 v162, v210, v76, vcc
	v_max_f32_e32 v78, v160, v162
	v_max_f32_e32 v76, v137, v139
	v_max_f32_e32 v77, v156, v157
	v_max3_f32 v78, v158, v159, v78
	v_max3_f32 v80, v76, v77, v78
	v_mov_b32_e32 v81, v80
	v_mfma_f32_16x16x32_bf16 v[40:43], v[72:75], v[164:167], v[40:43]
	ds_read2_b64 v[76:79], v2 offset0:8 offset1:12
	ds_read2_b64 v[72:75], v100 offset0:40 offset1:44
	s_waitcnt lgkmcnt(2)
	v_permlane16_swap_b32_e32 v81, v80
	v_max_f32_e32 v2, v80, v81
	v_mov_b32_e32 v96, v2
	ds_read2_b64 v[92:95], v3 offset0:72 offset1:76
	ds_read2_b64 v[88:91], v135 offset0:104 offset1:108
	ds_read2_b64 v[84:87], v136 offset0:136 offset1:140
	ds_read2_b64 v[80:83], v138 offset0:168 offset1:172
	v_mfma_f32_16x16x32_bf16 v[36:39], v[68:71], v[164:167], v[36:39]
	s_waitcnt lgkmcnt(4)
	v_permlane32_swap_b32_e32 v96, v2
	v_max_f32_e32 v2, v2, v96
	v_add_f32_e32 v3, 0x41000000, v154
	v_cmp_gt_f32_e32 vcc, v2, v3
	s_cmp_eq_u64 vcc, 0
	v_max_f32_e32 v3, v154, v154
	v_max_f32_e32 v2, v3, v2
	s_cselect_b64 vcc, -1, 0
	v_cndmask_b32_e32 v126, v2, v154, vcc
	v_sub_f32_e32 v2, v154, v126
	v_exp_f32_e32 v2, v2
	ds_read2_b64 v[100:103], v103 offset0:200 offset1:204
	ds_read2_b64 v[96:99], v155 offset0:232 offset1:236
	v_cmp_neq_f32_e32 vcc, 1.0, v2
	s_cbranch_vccz .LBB0_168
	v_pk_mul_f32 v[66:67], v[66:67], v[2:3] op_sel_hi:[1,0]
	v_pk_mul_f32 v[64:65], v[64:65], v[2:3] op_sel_hi:[1,0]
	v_pk_mul_f32 v[62:63], v[62:63], v[2:3] op_sel_hi:[1,0]
	v_pk_mul_f32 v[60:61], v[60:61], v[2:3] op_sel_hi:[1,0]
	v_pk_mul_f32 v[58:59], v[58:59], v[2:3] op_sel_hi:[1,0]
	v_pk_mul_f32 v[56:57], v[56:57], v[2:3] op_sel_hi:[1,0]
	v_pk_mul_f32 v[54:55], v[54:55], v[2:3] op_sel_hi:[1,0]
	v_pk_mul_f32 v[52:53], v[52:53], v[2:3] op_sel_hi:[1,0]
	v_pk_mul_f32 v[50:51], v[50:51], v[2:3] op_sel_hi:[1,0]
	v_pk_mul_f32 v[48:49], v[48:49], v[2:3] op_sel_hi:[1,0]
	v_pk_mul_f32 v[46:47], v[46:47], v[2:3] op_sel_hi:[1,0]
	v_pk_mul_f32 v[44:45], v[44:45], v[2:3] op_sel_hi:[1,0]
	v_pk_mul_f32 v[42:43], v[42:43], v[2:3] op_sel_hi:[1,0]
	v_pk_mul_f32 v[40:41], v[40:41], v[2:3] op_sel_hi:[1,0]
	v_pk_mul_f32 v[38:39], v[38:39], v[2:3] op_sel_hi:[1,0]
	v_pk_mul_f32 v[36:37], v[36:37], v[2:3] op_sel_hi:[1,0]

.LBB0_177:
	v_lshl_add_u64 v[2:3], s[22:23], 0, v[156:157]
	s_mov_b64 s[28:29], 0x2e850080
	v_lshl_add_u64 v[28:29], v[2:3], 0, s[28:29]
	v_lshl_add_u64 v[20:21], s[22:23], 0, v[158:159]
	s_mov_b64 s[28:29], 0x2de70000
	v_lshl_add_u64 v[30:31], v[20:21], 0, s[28:29]
	s_mov_b32 s28, 0x2de70000
	v_add_co_u32_e32 v20, vcc, s28, v20
	s_mov_b32 s28, 0x2e850000
	s_nop 0
	v_addc_co_u32_e32 v21, vcc, 0, v21, vcc
	v_add_co_u32_e32 v2, vcc, s28, v2
	s_and_b32 s28, 1, s13
	s_nop 0
	v_addc_co_u32_e32 v3, vcc, 0, v3, vcc
	global_load_dwordx4 v[20:23], v[20:21], off
	s_nop 0
	global_load_dwordx4 v[24:27], v[2:3], off offset:128
	global_load_dwordx4 v[32:35], v[30:31], off offset:16
	s_nop 0
	global_load_dwordx4 v[28:31], v[28:29], off offset:16
	s_cselect_b32 s29, 0, 0x8800
	s_add_i32 s29, s29, 0
	v_add_u32_e32 v0, s29, v163
	v_add_u32_e32 v199, v0, v165
	ds_read_b128 v[100:103], v199
	v_add_u32_e32 v192, v0, v164
	ds_read_b128 v[104:107], v192
	ds_read_b128 v[108:111], v199 offset:4096
	ds_read_b128 v[112:115], v192 offset:4096
	s_waitcnt vmcnt(5) lgkmcnt(1)
	v_mfma_f32_16x16x32_bf16 v[116:119], v[108:111], v[16:19], 0
	v_add_u32_e32 v2, s29, v162
	v_add_u32_e32 v189, v2, v155
	v_add_u32_e32 v193, v0, v169
	v_mfma_f32_16x16x32_bf16 v[100:103], v[100:103], v[16:19], 0
	v_add_u32_e32 v160, v0, v168
	ds_read_b128 v[120:123], v193
	ds_read_b128 v[136:139], v193 offset:4096
	ds_read_b128 v[124:127], v160
	ds_read_b128 v[224:227], v160 offset:4096
	v_add_u32_e32 v194, 0x4000, v189
	s_waitcnt lgkmcnt(4)
	v_mfma_f32_16x16x32_bf16 v[128:131], v[112:115], v[12:15], v[116:119]
	v_add_u32_e32 v196, 0x4800, v189
	v_add_u32_e32 v198, 0x5000, v189
	v_add_u32_e32 v195, 0x5800, v189
	v_mfma_f32_16x16x32_bf16 v[100:103], v[104:107], v[12:15], v[100:103]
	v_add_u32_e32 v201, 0x6000, v189
	s_nop 2
	v_mul_f32_e32 v188, 0x3e38aa3b, v130
	v_mul_f32_e32 v2, 0x3e38aa3b, v131
	v_mul_f32_e32 v186, 0x3e38aa3b, v128
	v_mul_f32_e32 v187, 0x3e38aa3b, v129
	v_mul_f32_e32 v3, 0x3e38aa3b, v100
	v_mul_f32_e32 v172, 0x3e38aa3b, v101
	v_mul_f32_e32 v173, 0x3e38aa3b, v102
	v_mul_f32_e32 v185, 0x3e38aa3b, v103
	v_max_f32_e32 v101, v188, v2
	v_max_f32_e32 v0, v3, v172
	v_max_f32_e32 v100, v173, v185
	v_max3_f32 v101, v186, v187, v101
	v_max3_f32 v0, v0, v100, v101
	v_mov_b32_e32 v100, v0
	s_waitcnt lgkmcnt(3)
	v_mfma_f32_16x16x32_bf16 v[132:135], v[120:123], v[8:11], 0
	v_add_u32_e32 v202, 0x6800, v189
	v_add_u32_e32 v200, 0x7000, v189
	v_add_u32_e32 v205, 0x7800, v189
	s_waitcnt lgkmcnt(0)
	v_permlane16_swap_b32_e32 v100, v0
	v_max_f32_e32 v0, v0, v100
	v_mov_b32_e32 v100, v0
	v_mfma_f32_16x16x32_bf16 v[136:139], v[136:139], v[8:11], 0
	ds_read2_b64 v[104:107], v194 offset1:4
	ds_read2_b64 v[108:111], v196 offset0:32 offset1:36
	ds_read2_b64 v[112:115], v198 offset0:64 offset1:68
	s_waitcnt lgkmcnt(3)
	v_permlane32_swap_b32_e32 v100, v0
	v_max_f32_e32 v0, v0, v100
	v_add_f32_e32 v100, 0x41000000, v171
	v_cmp_gt_f32_e32 vcc, v0, v100
	s_cmp_eq_u64 vcc, 0
	v_max_f32_e32 v100, v171, v171
	v_max_f32_e32 v0, v100, v0
	s_cselect_b64 vcc, -1, 0
	v_cndmask_b32_e32 v203, v0, v171, vcc
	v_sub_f32_e32 v0, v171, v203
	ds_read2_b64 v[116:119], v195 offset0:96 offset1:100
	ds_read2_b64 v[120:123], v201 offset0:128 offset1:132
	s_waitcnt vmcnt(4)
	v_mfma_f32_16x16x32_bf16 v[132:135], v[124:127], v[4:7], v[132:135]
	ds_read2_b64 v[128:131], v202 offset0:160 offset1:164
	ds_read2_b64 v[124:127], v200 offset0:192 offset1:196
	v_exp_f32_e32 v0, v0
	ds_read2_b64 v[100:103], v205 offset0:224 offset1:228
	v_mfma_f32_16x16x32_bf16 v[136:139], v[224:227], v[4:7], v[136:139]
	v_cmp_neq_f32_e32 vcc, 1.0, v0
	s_cbranch_vccz .LBB0_179
	v_pk_mul_f32 v[78:79], v[78:79], v[0:1] op_sel_hi:[1,0]
	v_pk_mul_f32 v[76:77], v[76:77], v[0:1] op_sel_hi:[1,0]
	v_pk_mul_f32 v[74:75], v[74:75], v[0:1] op_sel_hi:[1,0]
	v_pk_mul_f32 v[72:73], v[72:73], v[0:1] op_sel_hi:[1,0]
	v_pk_mul_f32 v[66:67], v[66:67], v[0:1] op_sel_hi:[1,0]
	v_pk_mul_f32 v[64:65], v[64:65], v[0:1] op_sel_hi:[1,0]
	v_pk_mul_f32 v[62:63], v[62:63], v[0:1] op_sel_hi:[1,0]
	v_pk_mul_f32 v[60:61], v[60:61], v[0:1] op_sel_hi:[1,0]
	v_pk_mul_f32 v[58:59], v[58:59], v[0:1] op_sel_hi:[1,0]
	v_pk_mul_f32 v[56:57], v[56:57], v[0:1] op_sel_hi:[1,0]
	v_pk_mul_f32 v[54:55], v[54:55], v[0:1] op_sel_hi:[1,0]
	v_pk_mul_f32 v[52:53], v[52:53], v[0:1] op_sel_hi:[1,0]
	v_pk_mul_f32 v[50:51], v[50:51], v[0:1] op_sel_hi:[1,0]
	v_pk_mul_f32 v[48:49], v[48:49], v[0:1] op_sel_hi:[1,0]
	v_pk_mul_f32 v[42:43], v[42:43], v[0:1] op_sel_hi:[1,0]
	v_pk_mul_f32 v[40:41], v[40:41], v[0:1] op_sel_hi:[1,0]

.LBB0_183:
	v_mul_f32_e32 v203, 0x3e38aa3b, v133
	v_mul_f32_e32 v202, 0x3e38aa3b, v134
	v_mul_f32_e32 v134, 0x3e38aa3b, v138
	s_nop 2
	v_mul_f32_e32 v133, 0x3e38aa3b, v139
	v_mul_f32_e32 v205, 0x3e38aa3b, v132
	v_mul_f32_e32 v201, 0x3e38aa3b, v135
	v_mul_f32_e32 v136, 0x3e38aa3b, v136
	v_mul_f32_e32 v135, 0x3e38aa3b, v137
	v_max_f32_e32 v138, v134, v133
	v_max_f32_e32 v132, v205, v203
	v_max_f32_e32 v137, v202, v201
	v_max3_f32 v138, v136, v135, v138
	v_max3_f32 v132, v132, v137, v138
	v_mov_b32_e32 v137, v132
	v_sub_f32_e32 v170, v170, v171
	v_sub_f32_e32 v192, v192, v171
	v_sub_f32_e32 v193, v193, v171
	v_sub_f32_e32 v194, v235, v171
	s_waitcnt lgkmcnt(0)
	v_permlane16_swap_b32_e32 v137, v132
	v_max_f32_e32 v132, v132, v137
	v_mov_b32_e32 v137, v132
	v_sub_f32_e32 v195, v233, v171
	v_sub_f32_e32 v196, v234, v171
	v_sub_f32_e32 v198, v199, v171
	v_exp_f32_e32 v199, v170
	s_waitcnt lgkmcnt(0)
	v_permlane32_swap_b32_e32 v137, v132
	v_max_f32_e32 v132, v132, v137
	v_add_f32_e32 v137, 0x41000000, v204
	v_sub_f32_e32 v170, v232, v171
	v_cmp_gt_f32_e32 vcc, v132, v137
	v_exp_f32_e32 v192, v192
	v_exp_f32_e32 v193, v193
	v_exp_f32_e32 v194, v194
	v_exp_f32_e32 v195, v195
	v_exp_f32_e32 v196, v196
	v_exp_f32_e32 v198, v198
	v_exp_f32_e32 v200, v170
	s_cmp_eq_u64 vcc, 0
	v_max_f32_e32 v137, v204, v204
	s_cselect_b64 vcc, -1, 0
	v_max_f32_e32 v132, v137, v132
	v_cndmask_b32_e32 v170, v132, v204, vcc
	v_sub_f32_e32 v132, v204, v170
	v_cvt_pk_bf16_f32 v232, v192, v193
	v_cvt_pk_bf16_f32 v233, v194, v195
	v_cvt_pk_bf16_f32 v234, v196, v198
	v_cvt_pk_bf16_f32 v235, v199, v200
	v_exp_f32_e32 v132, v132
	s_nop 0
	v_mfma_f32_16x16x32_bf16 v[76:79], v[128:131], v[232:235], v[76:79]
	v_cmp_neq_f32_e32 vcc, 1.0, v132
	v_mfma_f32_16x16x32_bf16 v[72:75], v[124:127], v[232:235], v[72:75]
	v_mfma_f32_16x16x32_bf16 v[64:67], v[120:123], v[232:235], v[64:67]
	v_mfma_f32_16x16x32_bf16 v[60:63], v[116:119], v[232:235], v[60:63]
	v_mfma_f32_16x16x32_bf16 v[56:59], v[112:115], v[232:235], v[56:59]
	v_mfma_f32_16x16x32_bf16 v[52:55], v[104:107], v[232:235], v[52:55]
	v_mfma_f32_16x16x32_bf16 v[48:51], v[108:111], v[232:235], v[48:51]
	v_mfma_f32_16x16x32_bf16 v[40:43], v[100:103], v[232:235], v[40:43]
	s_cbranch_vccz .LBB0_176
	v_pk_mul_f32 v[46:47], v[46:47], v[132:133] op_sel_hi:[1,0]
	v_pk_mul_f32 v[44:45], v[44:45], v[132:133] op_sel_hi:[1,0]
	v_pk_mul_f32 v[70:71], v[70:71], v[132:133] op_sel_hi:[1,0]
	v_pk_mul_f32 v[68:69], v[68:69], v[132:133] op_sel_hi:[1,0]
	v_pk_mul_f32 v[82:83], v[82:83], v[132:133] op_sel_hi:[1,0]
	v_pk_mul_f32 v[80:81], v[80:81], v[132:133] op_sel_hi:[1,0]
	v_pk_mul_f32 v[86:87], v[86:87], v[132:133] op_sel_hi:[1,0]
	v_pk_mul_f32 v[84:85], v[84:85], v[132:133] op_sel_hi:[1,0]
	v_pk_mul_f32 v[90:91], v[90:91], v[132:133] op_sel_hi:[1,0]
	v_pk_mul_f32 v[88:89], v[88:89], v[132:133] op_sel_hi:[1,0]
	v_pk_mul_f32 v[94:95], v[94:95], v[132:133] op_sel_hi:[1,0]
	v_pk_mul_f32 v[92:93], v[92:93], v[132:133] op_sel_hi:[1,0]
	v_pk_mul_f32 v[98:99], v[98:99], v[132:133] op_sel_hi:[1,0]
	v_pk_mul_f32 v[96:97], v[96:97], v[132:133] op_sel_hi:[1,0]
	v_pk_mul_f32 v[38:39], v[38:39], v[132:133] op_sel_hi:[1,0]
	v_pk_mul_f32 v[36:37], v[36:37], v[132:133] op_sel_hi:[1,0]
	s_branch .LBB0_176
.LBB0_185:
	v_add_u32_e32 v3, s28, v163
	v_add_u32_e32 v139, v3, v165
	ds_read_b128 v[20:23], v139
	v_add_u32_e32 v0, v3, v164
	ds_read_b128 v[24:27], v0
	ds_read_b128 v[28:31], v139 offset:4096
	ds_read_b128 v[32:35], v0 offset:4096
	s_waitcnt lgkmcnt(1)
	v_mfma_f32_16x16x32_bf16 v[28:31], v[28:31], v[16:19], 0
	v_add_u32_e32 v2, v3, v169
	v_add_u32_e32 v3, v3, v168
	ds_read_b128 v[100:103], v2
	ds_read_b128 v[108:111], v2 offset:4096
	ds_read_b128 v[120:123], v3
	ds_read_b128 v[128:131], v3 offset:4096
	v_mfma_f32_16x16x32_bf16 v[20:23], v[20:23], v[16:19], 0
	v_add_u32_e32 v104, s28, v162
	v_add_u32_e32 v134, v104, v155
	v_add_u32_e32 v133, 0x4000, v134
	s_waitcnt lgkmcnt(4)
	v_mfma_f32_16x16x32_bf16 v[32:35], v[32:35], v[12:15], v[28:31]
	v_add_u32_e32 v137, 0x4800, v134
	v_add_u32_e32 v155, 0x5000, v134
	v_add_u32_e32 v135, 0x5800, v134
	v_mfma_f32_16x16x32_bf16 v[116:119], v[24:27], v[12:15], v[20:23]
	v_add_u32_e32 v159, 0x6000, v134
	v_add_u32_e32 v163, 0x6800, v134
	v_add_u32_e32 v157, 0x7000, v134
	s_waitcnt lgkmcnt(3)
	v_mfma_f32_16x16x32_bf16 v[124:127], v[100:103], v[8:11], 0
	v_mul_f32_e32 v101, 0x3e38aa3b, v34
	v_mul_f32_e32 v100, 0x3e38aa3b, v35
	s_nop 0
	v_mul_f32_e32 v107, 0x3e38aa3b, v116
	v_mul_f32_e32 v106, 0x3e38aa3b, v117
	v_mul_f32_e32 v105, 0x3e38aa3b, v118
	v_mul_f32_e32 v104, 0x3e38aa3b, v119
	v_mul_f32_e32 v103, 0x3e38aa3b, v32
	v_mul_f32_e32 v102, 0x3e38aa3b, v33
	v_max_f32_e32 v34, v101, v100
	v_max_f32_e32 v32, v107, v106
	v_max_f32_e32 v33, v105, v104
	v_max3_f32 v34, v103, v102, v34
	v_max3_f32 v132, v32, v33, v34
	ds_bpermute_b32 v136, v179, v132
	s_waitcnt lgkmcnt(2)
	v_mfma_f32_16x16x32_bf16 v[32:35], v[120:123], v[4:7], v[124:127]
	v_add_u32_e32 v169, 0x7800, v134
	ds_read2_b64 v[20:23], v133 offset1:4
	ds_read2_b64 v[24:27], v137 offset0:32 offset1:36
	s_waitcnt lgkmcnt(2)
	v_max_f32_e32 v120, v136, v136
	v_max_f32_e32 v132, v132, v120
	ds_bpermute_b32 v136, v178, v132
	v_mfma_f32_16x16x32_bf16 v[186:189], v[108:111], v[8:11], 0
	v_add_f32_e32 v109, 0x41000000, v171
	ds_read2_b64 v[28:31], v155 offset0:64 offset1:68
	ds_read2_b64 v[112:115], v135 offset0:96 offset1:100
	s_waitcnt lgkmcnt(2)
	v_max_f32_e32 v108, v136, v136
	v_max_f32_e32 v108, v132, v108
	v_cmp_gt_f32_e32 vcc, v108, v109
	s_cmp_eq_u64 vcc, 0
	v_max_f32_e32 v109, v171, v171
	v_max_f32_e32 v108, v109, v108
	s_cselect_b64 vcc, -1, 0
	v_cndmask_b32_e32 v165, v108, v171, vcc
	v_sub_f32_e32 v108, v171, v165
	ds_read2_b64 v[116:119], v159 offset0:128 offset1:132
	ds_read2_b64 v[124:127], v163 offset0:160 offset1:164
	ds_read2_b64 v[120:123], v157 offset0:192 offset1:196
	v_exp_f32_e32 v132, v108
	ds_read2_b64 v[108:111], v169 offset0:224 offset1:228
	v_mfma_f32_16x16x32_bf16 v[128:131], v[128:131], v[4:7], v[186:189]
	v_cmp_neq_f32_e32 vcc, 1.0, v132
	s_cbranch_vccz .LBB0_187
	v_pk_mul_f32 v[78:79], v[78:79], v[132:133] op_sel_hi:[1,0]
	v_pk_mul_f32 v[76:77], v[76:77], v[132:133] op_sel_hi:[1,0]
	v_pk_mul_f32 v[74:75], v[74:75], v[132:133] op_sel_hi:[1,0]
	v_pk_mul_f32 v[72:73], v[72:73], v[132:133] op_sel_hi:[1,0]
	v_pk_mul_f32 v[66:67], v[66:67], v[132:133] op_sel_hi:[1,0]
	v_pk_mul_f32 v[64:65], v[64:65], v[132:133] op_sel_hi:[1,0]
	v_pk_mul_f32 v[62:63], v[62:63], v[132:133] op_sel_hi:[1,0]
	v_pk_mul_f32 v[60:61], v[60:61], v[132:133] op_sel_hi:[1,0]
	v_pk_mul_f32 v[58:59], v[58:59], v[132:133] op_sel_hi:[1,0]
	v_pk_mul_f32 v[56:57], v[56:57], v[132:133] op_sel_hi:[1,0]
	v_pk_mul_f32 v[54:55], v[54:55], v[132:133] op_sel_hi:[1,0]
	v_pk_mul_f32 v[52:53], v[52:53], v[132:133] op_sel_hi:[1,0]
	v_pk_mul_f32 v[50:51], v[50:51], v[132:133] op_sel_hi:[1,0]
	v_pk_mul_f32 v[48:49], v[48:49], v[132:133] op_sel_hi:[1,0]
	v_pk_mul_f32 v[42:43], v[42:43], v[132:133] op_sel_hi:[1,0]
	v_pk_mul_f32 v[40:41], v[40:41], v[132:133] op_sel_hi:[1,0]
